# P0 adaLN GEMV item: all 8 weight-row loads of an iteration issued up front into own register quads (was serialized through one quad)
# baseline (speedup 1.0000x reference)
.LBB0_111:
	v_add_co_u32_e32 v2, vcc, 0xfffac000, v64
	s_add_u32 s6, s2, s0
	s_nop 0
	v_addc_co_u32_e32 v3, vcc, -1, v65, vcc
	s_addc_u32 s7, s3, s1
	global_load_dwordx4 v[108:111], v[2:3], off
	v_add_co_u32_e32 v160, vcc, s90, v64
	s_nop 1
	v_addc_co_u32_e32 v161, vcc, -1, v65, vcc
	global_load_dwordx4 v[160:163], v[160:161], off
	v_add_co_u32_e32 v164, vcc, s91, v64
	s_nop 1
	v_addc_co_u32_e32 v165, vcc, -1, v65, vcc
	global_load_dwordx4 v[164:167], v[164:165], off
	v_add_co_u32_e32 v168, vcc, s92, v64
	s_nop 1
	v_addc_co_u32_e32 v169, vcc, -1, v65, vcc
	global_load_dwordx4 v[168:171], v[168:169], off
	v_add_co_u32_e32 v172, vcc, s93, v64
	s_nop 1
	v_addc_co_u32_e32 v173, vcc, -1, v65, vcc
	global_load_dwordx4 v[172:175], v[172:173], off
	v_add_co_u32_e32 v176, vcc, s94, v64
	s_nop 1
	v_addc_co_u32_e32 v177, vcc, -1, v65, vcc
	global_load_dwordx4 v[176:179], v[176:177], off
	v_add_co_u32_e32 v180, vcc, s95, v64
	s_nop 1
	v_addc_co_u32_e32 v181, vcc, -1, v65, vcc
	global_load_dwordx4 v[180:183], v[180:181], off
	global_load_dwordx4 v[184:187], v[64:65], off
	global_load_dwordx4 v[10:13], v15, s[6:7] offset:16
	global_load_dwordx4 v[112:115], v15, s[6:7]
	s_add_u32 s10, s6, 0x2000
	s_addc_u32 s11, s7, 0
	global_load_dwordx4 v[6:9], v15, s[10:11] offset:16
	global_load_dwordx4 v[116:119], v105, s[6:7]
	s_add_u32 s6, s4, s0
	s_addc_u32 s7, s5, s1
	global_load_dwordx4 v[2:5], v15, s[6:7] offset:16
	global_load_dwordx4 v[120:123], v15, s[6:7]
	s_add_u32 s0, s0, 32
	s_addc_u32 s1, s1, 0
	s_cmpk_eq_i32 s0, 0x100
	s_waitcnt vmcnt(4)
	v_mul_f32_e32 v14, 0xbfb8aa3b, v112
	v_exp_f32_e32 v14, v14
	s_nop 0
	v_add_f32_e32 v14, 1.0, v14
	v_rcp_f32_e32 v14, v14
	s_nop 0
	v_mul_f32_e32 v14, v112, v14
	v_pk_fma_f32 v[126:127], v[110:111], v[14:15], v[66:67] op_sel_hi:[1,0,1]
	v_pk_fma_f32 v[124:125], v[108:109], v[14:15], v[68:69] op_sel_hi:[1,0,1]
	s_waitcnt vmcnt(2)
	v_mul_f32_e32 v14, 0xbfb8aa3b, v116
	v_exp_f32_e32 v14, v14
	s_nop 0
	v_add_f32_e32 v14, 1.0, v14
	v_rcp_f32_e32 v14, v14
	s_nop 0
	v_mul_f32_e32 v14, v116, v14
	v_pk_fma_f32 v[74:75], v[108:109], v[14:15], v[74:75] op_sel_hi:[1,0,1]
	v_pk_fma_f32 v[70:71], v[110:111], v[14:15], v[70:71] op_sel_hi:[1,0,1]
	s_waitcnt vmcnt(0)
	v_mul_f32_e32 v14, 0xbfb8aa3b, v120
	v_exp_f32_e32 v14, v14
	s_nop 0
	v_add_f32_e32 v14, 1.0, v14
	v_rcp_f32_e32 v14, v14
	s_nop 0
	v_mul_f32_e32 v14, v120, v14
	v_pk_fma_f32 v[76:77], v[108:109], v[14:15], v[76:77] op_sel_hi:[1,0,1]
	v_pk_fma_f32 v[72:73], v[110:111], v[14:15], v[72:73] op_sel_hi:[1,0,1]
	v_mul_f32_e32 v14, 0xbfb8aa3b, v113
	v_exp_f32_e32 v14, v14
	s_nop 0
	v_add_f32_e32 v14, 1.0, v14
	v_rcp_f32_e32 v14, v14
	s_nop 0
	v_mul_f32_e32 v14, v113, v14
	v_pk_fma_f32 v[108:109], v[162:163], v[14:15], v[126:127] op_sel_hi:[1,0,1]
	v_pk_fma_f32 v[110:111], v[160:161], v[14:15], v[124:125] op_sel_hi:[1,0,1]
	v_mul_f32_e32 v14, 0xbfb8aa3b, v117
	v_exp_f32_e32 v14, v14
	s_nop 0
	v_add_f32_e32 v14, 1.0, v14
	v_rcp_f32_e32 v14, v14
	s_nop 0
	v_mul_f32_e32 v14, v117, v14
	v_pk_fma_f32 v[70:71], v[162:163], v[14:15], v[70:71] op_sel_hi:[1,0,1]
	v_pk_fma_f32 v[74:75], v[160:161], v[14:15], v[74:75] op_sel_hi:[1,0,1]
	v_mul_f32_e32 v14, 0xbfb8aa3b, v121
	v_exp_f32_e32 v14, v14
	s_nop 0
	v_add_f32_e32 v14, 1.0, v14
	v_rcp_f32_e32 v14, v14
	s_nop 0
	v_mul_f32_e32 v14, v121, v14
	v_pk_fma_f32 v[76:77], v[160:161], v[14:15], v[76:77] op_sel_hi:[1,0,1]
	v_pk_fma_f32 v[72:73], v[162:163], v[14:15], v[72:73] op_sel_hi:[1,0,1]
	v_mul_f32_e32 v14, 0xbfb8aa3b, v114
	v_exp_f32_e32 v14, v14
	s_nop 0
	v_add_f32_e32 v14, 1.0, v14
	v_rcp_f32_e32 v14, v14
	s_nop 0
	v_mul_f32_e32 v14, v114, v14
	v_pk_fma_f32 v[108:109], v[166:167], v[14:15], v[108:109] op_sel_hi:[1,0,1]
	v_pk_fma_f32 v[110:111], v[164:165], v[14:15], v[110:111] op_sel_hi:[1,0,1]
	v_mul_f32_e32 v14, 0xbfb8aa3b, v118
	v_exp_f32_e32 v14, v14
	s_nop 0
	v_add_f32_e32 v14, 1.0, v14
	v_rcp_f32_e32 v14, v14
	s_nop 0
	v_mul_f32_e32 v14, v118, v14
	v_pk_fma_f32 v[70:71], v[166:167], v[14:15], v[70:71] op_sel_hi:[1,0,1]
	v_pk_fma_f32 v[74:75], v[164:165], v[14:15], v[74:75] op_sel_hi:[1,0,1]
	v_mul_f32_e32 v14, 0xbfb8aa3b, v122
	v_exp_f32_e32 v14, v14
	s_nop 0
	v_add_f32_e32 v14, 1.0, v14
	v_rcp_f32_e32 v14, v14
	s_nop 0
	v_mul_f32_e32 v14, v122, v14
	v_pk_fma_f32 v[76:77], v[164:165], v[14:15], v[76:77] op_sel_hi:[1,0,1]
	v_pk_fma_f32 v[72:73], v[166:167], v[14:15], v[72:73] op_sel_hi:[1,0,1]
	v_mul_f32_e32 v14, 0xbfb8aa3b, v115
	v_exp_f32_e32 v14, v14
	s_nop 0
	v_add_f32_e32 v14, 1.0, v14
	v_rcp_f32_e32 v14, v14
	s_nop 0
	v_mul_f32_e32 v14, v115, v14
	v_pk_fma_f32 v[108:109], v[170:171], v[14:15], v[108:109] op_sel_hi:[1,0,1]
	v_pk_fma_f32 v[110:111], v[168:169], v[14:15], v[110:111] op_sel_hi:[1,0,1]
	v_mul_f32_e32 v14, 0xbfb8aa3b, v119
	v_exp_f32_e32 v14, v14
	s_nop 0
	v_add_f32_e32 v14, 1.0, v14
	v_rcp_f32_e32 v14, v14
	s_nop 0
	v_mul_f32_e32 v14, v119, v14
	v_pk_fma_f32 v[70:71], v[170:171], v[14:15], v[70:71] op_sel_hi:[1,0,1]
	v_pk_fma_f32 v[74:75], v[168:169], v[14:15], v[74:75] op_sel_hi:[1,0,1]
	v_mul_f32_e32 v14, 0xbfb8aa3b, v123
	v_exp_f32_e32 v14, v14
	s_nop 0
	v_add_f32_e32 v14, 1.0, v14
	v_rcp_f32_e32 v14, v14
	s_nop 0
	v_mul_f32_e32 v14, v123, v14
	v_pk_fma_f32 v[76:77], v[168:169], v[14:15], v[76:77] op_sel_hi:[1,0,1]
	v_pk_fma_f32 v[72:73], v[170:171], v[14:15], v[72:73] op_sel_hi:[1,0,1]
	v_mul_f32_e32 v14, 0xbfb8aa3b, v10
	v_exp_f32_e32 v14, v14
	s_nop 0
	v_add_f32_e32 v14, 1.0, v14
	v_rcp_f32_e32 v14, v14
	s_nop 0
	v_mul_f32_e32 v10, v10, v14
	v_mul_f32_e32 v14, 0xbfb8aa3b, v12
	v_exp_f32_e32 v14, v14
	v_pk_fma_f32 v[108:109], v[174:175], v[10:11], v[108:109] op_sel_hi:[1,0,1]
	v_pk_fma_f32 v[110:111], v[172:173], v[10:11], v[110:111] op_sel_hi:[1,0,1]
	v_mul_f32_e32 v10, 0xbfb8aa3b, v6
	v_exp_f32_e32 v10, v10
	v_add_f32_e32 v14, 1.0, v14
	v_rcp_f32_e32 v14, v14
	v_add_f32_e32 v10, 1.0, v10
	v_rcp_f32_e32 v10, v10
	v_mul_f32_e32 v12, v12, v14
	v_mul_f32_e32 v6, v6, v10
	v_pk_fma_f32 v[70:71], v[174:175], v[6:7], v[70:71] op_sel_hi:[1,0,1]
	v_pk_fma_f32 v[74:75], v[172:173], v[6:7], v[74:75] op_sel_hi:[1,0,1]
	v_mul_f32_e32 v6, 0xbfb8aa3b, v2
	v_exp_f32_e32 v6, v6
	s_nop 0
	v_add_f32_e32 v6, 1.0, v6
	v_rcp_f32_e32 v6, v6
	s_nop 0
	v_mul_f32_e32 v2, v2, v6
	v_pk_fma_f32 v[76:77], v[172:173], v[2:3], v[76:77] op_sel_hi:[1,0,1]
	v_pk_fma_f32 v[72:73], v[174:175], v[2:3], v[72:73] op_sel_hi:[1,0,1]
	v_mul_f32_e32 v2, 0xbfb8aa3b, v11
	v_exp_f32_e32 v2, v2
	s_nop 0
	v_add_f32_e32 v2, 1.0, v2
	v_rcp_f32_e32 v2, v2
	s_nop 0
	v_mul_f32_e32 v2, v11, v2
	v_pk_fma_f32 v[10:11], v[178:179], v[2:3], v[108:109] op_sel_hi:[1,0,1]
	v_pk_fma_f32 v[108:109], v[176:177], v[2:3], v[110:111] op_sel_hi:[1,0,1]
	v_mul_f32_e32 v2, 0xbfb8aa3b, v7
	v_exp_f32_e32 v2, v2
	s_nop 0
	v_add_f32_e32 v2, 1.0, v2
	v_rcp_f32_e32 v2, v2
	s_nop 0
	v_mul_f32_e32 v2, v7, v2
	v_pk_fma_f32 v[6:7], v[178:179], v[2:3], v[70:71] op_sel_hi:[1,0,1]
	v_pk_fma_f32 v[70:71], v[176:177], v[2:3], v[74:75] op_sel_hi:[1,0,1]
	v_mul_f32_e32 v2, 0xbfb8aa3b, v3
	v_exp_f32_e32 v2, v2
	s_nop 0
	v_add_f32_e32 v2, 1.0, v2
	v_rcp_f32_e32 v2, v2
	s_nop 0
	v_mul_f32_e32 v2, v3, v2
	v_pk_fma_f32 v[72:73], v[178:179], v[2:3], v[72:73] op_sel_hi:[1,0,1]
	v_pk_fma_f32 v[2:3], v[176:177], v[2:3], v[76:77] op_sel_hi:[1,0,1]
	v_pk_fma_f32 v[74:75], v[180:181], v[12:13], v[108:109] op_sel_hi:[1,0,1]
	v_pk_fma_f32 v[10:11], v[182:183], v[12:13], v[10:11] op_sel_hi:[1,0,1]
	v_mul_f32_e32 v12, 0xbfb8aa3b, v8
	v_exp_f32_e32 v12, v12
	v_lshl_add_u64 v[64:65], v[64:65], 0, s[22:23]
	v_add_f32_e32 v12, 1.0, v12
	v_rcp_f32_e32 v12, v12
	s_nop 0
	v_mul_f32_e32 v8, v8, v12
	v_pk_fma_f32 v[6:7], v[182:183], v[8:9], v[6:7] op_sel_hi:[1,0,1]
	v_pk_fma_f32 v[76:77], v[180:181], v[8:9], v[70:71] op_sel_hi:[1,0,1]
	v_mul_f32_e32 v8, 0xbfb8aa3b, v4
	v_exp_f32_e32 v8, v8
	s_nop 0
	v_add_f32_e32 v8, 1.0, v8
	v_rcp_f32_e32 v8, v8
	s_nop 0
	v_mul_f32_e32 v4, v4, v8
	v_pk_fma_f32 v[72:73], v[182:183], v[4:5], v[72:73] op_sel_hi:[1,0,1]
	v_pk_fma_f32 v[2:3], v[180:181], v[4:5], v[2:3] op_sel_hi:[1,0,1]
	v_mul_f32_e32 v4, 0xbfb8aa3b, v13
	v_exp_f32_e32 v4, v4
	s_nop 0
	v_add_f32_e32 v4, 1.0, v4
	v_rcp_f32_e32 v4, v4
	s_nop 0
	v_mul_f32_e32 v4, v13, v4
	v_pk_fma_f32 v[66:67], v[186:187], v[4:5], v[10:11] op_sel_hi:[1,0,1]
	v_pk_fma_f32 v[68:69], v[184:185], v[4:5], v[74:75] op_sel_hi:[1,0,1]
	v_mul_f32_e32 v4, 0xbfb8aa3b, v9
	v_exp_f32_e32 v4, v4
	s_nop 0
	v_add_f32_e32 v4, 1.0, v4
	v_rcp_f32_e32 v4, v4
	s_nop 0
	v_mul_f32_e32 v4, v9, v4
	v_pk_fma_f32 v[70:71], v[186:187], v[4:5], v[6:7] op_sel_hi:[1,0,1]
	v_pk_fma_f32 v[74:75], v[184:185], v[4:5], v[76:77] op_sel_hi:[1,0,1]
	v_mul_f32_e32 v4, 0xbfb8aa3b, v5
	v_exp_f32_e32 v4, v4
	s_nop 0
	v_add_f32_e32 v4, 1.0, v4
	v_rcp_f32_e32 v4, v4
	s_nop 0
	v_mul_f32_e32 v4, v5, v4
	v_pk_fma_f32 v[72:73], v[186:187], v[4:5], v[72:73] op_sel_hi:[1,0,1]
	v_pk_fma_f32 v[76:77], v[184:185], v[4:5], v[2:3] op_sel_hi:[1,0,1]
	s_cbranch_scc0 .LBB0_111
	v_lshlrev_b64 v[2:3], 2, v[62:63]
	v_lshl_add_u64 v[4:5], s[30:31], 0, v[2:3]
	v_lshl_add_u64 v[6:7], s[24:25], 0, v[2:3]
	v_lshl_add_u64 v[2:3], s[64:65], 0, v[2:3]
	global_atomic_add_f32 v[4:5], v68, off
	global_atomic_add_f32 v[6:7], v74, off
	global_atomic_add_f32 v[2:3], v76, off
	global_atomic_add_f32 v[4:5], v69, off offset:4
	global_atomic_add_f32 v[6:7], v75, off offset:4
	global_atomic_add_f32 v[2:3], v77, off offset:4
	global_atomic_add_f32 v[4:5], v66, off offset:8
	global_atomic_add_f32 v[6:7], v70, off offset:8
	global_atomic_add_f32 v[2:3], v72, off offset:8
	global_atomic_add_f32 v[4:5], v67, off offset:12
	global_atomic_add_f32 v[6:7], v71, off offset:12
	global_atomic_add_f32 v[2:3], v73, off offset:12
	s_branch .LBB0_8
